# v30 plus MLA loop top: the four post-barrier v_exp moved in front of the exit test and loop-back barrier
# baseline (speedup 1.0000x reference)
; #define SBAR() __builtin_amdgcn_sched_barrier(0)
; #define SLOAD(i, k0) do { st_[i].vs = *reinterpret_cast<const bf16x8*>(&Vh[(size_t)((k0) + sr) * LDK + sc]); \
;     st_[i].ks = *reinterpret_cast<const bf16x8*>(&Kh[(size_t)((k0) + sr) * LDK + sc]); \
;     if (DQ == 96) st_[i].kr = *reinterpret_cast<const bf16x8*>(&Kr[(size_t)((k0) + sr2) * 32 + sc2]); } while (0)
; #define SWRITE(b, i) do { *(bf16x8*)(V_lds + (b) * SHM_V + vst0) = st_[i].vs; *(bf16x8*)(K_lds + (b) * SHM_K + kst0) = st_[i].ks; \
;     if (DQ == 96) { if (tid < 256) *(bf16x8*)(K_lds + (b) * SHM_K + kst2) = st_[i].kr; } } while (0)
; #define SWAIT() do { if (DQ == 96) asm volatile("s_waitcnt vmcnt(3)" ::: "memory"); else asm volatile("s_waitcnt vmcnt(2)" ::: "memory"); } while (0)
; #define SLOAD(i, k0) do { st_[i].vs = *reinterpret_cast<const bf16x8*>(&Vh[(size_t)((k0) + sr) * LDK + sc]); \
;     st_[i].ks = *reinterpret_cast<const bf16x8*>(&Kh[(size_t)((k0) + sr) * LDK + sc]); \
;     if (DQ == 96) st_[i].kr = *reinterpret_cast<const bf16x8*>(&Kr[(size_t)((k0) + sr2) * 32 + sc2]); } while (0)
; #define SWRITE(b, i) do { *(bf16x8*)(V_lds + (b) * SHM_V + vst0) = st_[i].vs; *(bf16x8*)(K_lds + (b) * SHM_K + kst0) = st_[i].ks; \
;     if (DQ == 96) { if (tid < 256) *(bf16x8*)(K_lds + (b) * SHM_K + kst2) = st_[i].kr; } } while (0)
; #define SWAIT() do { if (DQ == 96) asm volatile("s_waitcnt vmcnt(3)" ::: "memory"); else asm volatile("s_waitcnt vmcnt(2)" ::: "memory"); } while (0)
; template <int DQ, bool WIN, int LDQ, int LDK> ...
;     ...
;         exp16(pB0);
;         __syncthreads();
;         SBAR(); qkt<DQ>(pA0, pA1, K_lds, qr, minit, r32, hi);
;         finish(pB0, pB1); SBAR();
;         if (j + 3 < NT) SLOAD(SE, KBASE(j + 3)); SBAR();
;         pv(vb0 + SHM_V);
;         __syncthreads(); SWAIT(); SWRITE(1, SO);
;         lsum_upd();
;         if (WIN) win_mask(pA0, pA1, qrow - KBASE(j + 1), hi);
;         exp16(pA0);
;         __syncthreads();
.LBB0_1093:
	v_xor_b32_e32 v192, 0xc000, v192
	v_xor_b32_e32 v194, 0xc000, v194
	v_xor_b32_e32 v190, 0xc000, v190
	v_exp_f32_e32 v161, v96
	v_exp_f32_e32 v196, v97
	v_mfma_f32_16x16x32_bf16 v[32:35], v[80:83], v[36:39], v[32:35]
	v_exp_f32_e32 v158, v98
	v_exp_f32_e32 v168, v99
	v_exp_f32_e32 v159, v100
	v_exp_f32_e32 v169, v101
	v_exp_f32_e32 v160, v102
	v_exp_f32_e32 v195, v103
	v_exp_f32_e32 v154, v105
	v_mfma_f32_16x16x32_bf16 v[32:35], v[84:87], v[36:39], v[32:35]
	v_exp_f32_e32 v155, v107
	v_exp_f32_e32 v156, v109
	v_exp_f32_e32 v157, v111
	v_lshl_add_u64 v[162:163], v[162:163], 0, s[34:35]
	v_lshl_add_u64 v[164:165], v[164:165], 0, s[18:19]
	v_mfma_f32_16x16x32_bf16 v[32:35], v[88:91], v[36:39], v[32:35]
	v_lshl_add_u64 v[166:167], v[166:167], 0, s[34:35]
	v_exp_f32_e32 v150, v104
	v_exp_f32_e32 v151, v106
	v_exp_f32_e32 v152, v108
	v_exp_f32_e32 v153, v110
	s_cmpk_gt_u32 s17, 0x7c
	s_cbranch_scc1 .Lmla_exit
	s_waitcnt lgkmcnt(0)
	s_barrier
	v_mfma_f32_16x16x32_bf16 v[32:35], v[92:95], v[36:39], v[32:35]

; #define SBAR() __builtin_amdgcn_sched_barrier(0)
; template <int DQ, bool WIN, int LDQ, int LDK> ...
;     ...
;     SBAR(); qkt<DQ>(pB0, pB1, K_lds + SHM_K, qr, minit, r32, hi);
;     finish(pA0, pA1); SBAR();
;     pv(vb0); lsum_upd();
;     if (WIN) win_mask(pB0, pB1, qrow - KBASE(NT - 1), hi);
;     exp16(pB0);
;     finish(pB0, pB1); SBAR();
;     pv(vb0 + SHM_V); lsum_upd();
.Lmla_exit:
	s_waitcnt lgkmcnt(0)
	s_barrier
	v_mfma_f32_16x16x32_bf16 v[32:35], v[92:95], v[36:39], v[32:35]
.LBB0_1100:
	ds_read_b128 v[96:99], v191 offset:29696
	v_exp_f32_e32 v79, v79
	v_exp_f32_e32 v112, v64
	s_waitcnt lgkmcnt(0)
	v_mfma_f32_32x32x16_bf16 v[80:95], v[96:99], v[134:137], v[48:63]
	ds_read_b128 v[96:99], v191 offset:36352
	s_waitcnt lgkmcnt(0)
	v_mfma_f32_32x32x16_bf16 v[48:63], v[96:99], v[134:137], v[48:63]
	ds_read_b128 v[96:99], v191 offset:29728
	s_waitcnt lgkmcnt(0)
	v_mfma_f32_32x32x16_bf16 v[80:95], v[96:99], v[130:133], v[80:95]
	ds_read_b128 v[96:99], v191 offset:36384
	s_waitcnt lgkmcnt(0)
	v_mfma_f32_32x32x16_bf16 v[48:63], v[96:99], v[130:133], v[48:63]
	ds_read_b128 v[96:99], v191 offset:29760
	v_exp_f32_e32 v130, v65
	v_exp_f32_e32 v131, v66
	s_waitcnt lgkmcnt(0)
	v_mfma_f32_32x32x16_bf16 v[80:95], v[96:99], v[126:129], v[80:95]
	ds_read_b128 v[96:99], v191 offset:36416
	s_waitcnt lgkmcnt(0)
	v_mfma_f32_32x32x16_bf16 v[48:63], v[96:99], v[126:129], v[48:63]
	ds_read_b128 v[96:99], v191 offset:29792
	ds_read_b128 v[100:103], v191 offset:36448
	s_waitcnt lgkmcnt(1)
	v_mfma_f32_32x32x16_bf16 v[80:95], v[96:99], v[122:125], v[80:95]
	ds_read_b128 v[96:99], v191 offset:29824
	ds_read_b128 v[104:107], v191 offset:29856
	ds_read_b128 v[108:111], v191 offset:36480
	ds_read_b128 v[126:129], v191 offset:36512
	v_cvt_pk_bf16_f32 v64, v161, v196
	v_cvt_pk_bf16_f32 v65, v158, v168
	v_cvt_pk_bf16_f32 v66, v159, v169
	s_waitcnt lgkmcnt(4)
	v_mfma_f32_32x32x16_bf16 v[48:63], v[100:103], v[122:125], v[48:63]
	v_exp_f32_e32 v100, v67
	v_exp_f32_e32 v101, v68
	v_exp_f32_e32 v102, v69
	v_exp_f32_e32 v103, v70
	v_exp_f32_e32 v122, v71
	v_exp_f32_e32 v123, v72
	v_exp_f32_e32 v124, v73
	s_waitcnt lgkmcnt(3)
	v_mfma_f32_32x32x16_bf16 v[80:95], v[96:99], v[118:121], v[80:95]
	v_exp_f32_e32 v96, v74
	v_exp_f32_e32 v97, v75
	v_exp_f32_e32 v98, v76
	v_exp_f32_e32 v99, v77
	v_exp_f32_e32 v125, v78
	v_cvt_pk_bf16_f32 v67, v160, v195
	v_cvt_pk_bf16_f32 v68, v150, v154
	s_waitcnt lgkmcnt(1)
	v_mfma_f32_32x32x16_bf16 v[48:63], v[108:111], v[118:121], v[48:63]
	v_cvt_pk_bf16_f32 v69, v151, v155
	v_cvt_pk_bf16_f32 v70, v152, v156
	v_cvt_pk_bf16_f32 v71, v153, v157
	v_cvt_pk_bf16_f32 v72, v112, v130
	v_cvt_pk_bf16_f32 v73, v131, v100
	v_cvt_pk_bf16_f32 v74, v101, v102
	v_cvt_pk_bf16_f32 v75, v103, v122
	v_mfma_f32_32x32x16_bf16 v[80:95], v[104:107], v[114:117], v[80:95]
	v_cvt_pk_bf16_f32 v76, v123, v124
	v_cvt_pk_bf16_f32 v77, v96, v97
	v_cvt_pk_bf16_f32 v78, v98, v99
	v_cvt_pk_bf16_f32 v79, v125, v79
	s_waitcnt lgkmcnt(0)
	v_mfma_f32_32x32x16_bf16 v[48:63], v[126:129], v[114:117], v[48:63]
	ds_read_b64_tr_b16 v[96:97], v194 offset:0
	ds_read_b64_tr_b16 v[98:99], v194 offset:0x400
	ds_read_b64_tr_b16 v[100:101], v194 offset:0x800
	ds_read_b64_tr_b16 v[102:103], v194 offset:0xc00
	ds_read_b64_tr_b16 v[104:105], v194 offset:0x1000
	ds_read_b64_tr_b16 v[106:107], v194 offset:0x1400
	ds_read_b64_tr_b16 v[108:109], v194 offset:0x1800
	ds_read_b64_tr_b16 v[110:111], v194 offset:0x1c00
	s_waitcnt lgkmcnt(0)
	s_nop 0
	v_mfma_f32_32x32x16_bf16 v[0:15], v[64:67], v[96:99], v[0:15]
	ds_read_b64_tr_b16 v[96:97], v194 offset:0x200
	ds_read_b64_tr_b16 v[98:99], v194 offset:0x600
	v_mfma_f32_32x32x16_bf16 v[0:15], v[68:71], v[100:103], v[0:15]
	ds_read_b64_tr_b16 v[100:101], v194 offset:0xa00
	ds_read_b64_tr_b16 v[102:103], v194 offset:0xe00
	v_mfma_f32_32x32x16_bf16 v[0:15], v[72:75], v[104:107], v[0:15]
	ds_read_b64_tr_b16 v[104:105], v194 offset:0x1200
	ds_read_b64_tr_b16 v[106:107], v194 offset:0x1600
	v_mfma_f32_32x32x16_bf16 v[0:15], v[76:79], v[108:111], v[0:15]
	ds_read_b64_tr_b16 v[108:109], v194 offset:0x1a00
	ds_read_b64_tr_b16 v[110:111], v194 offset:0x1e00
	s_waitcnt lgkmcnt(0)
	v_mfma_f32_32x32x16_bf16 v[16:31], v[64:67], v[96:99], v[16:31]
	s_nop 1
	s_nop 3
	v_exp_f32_e32 v63, v63
	v_mfma_f32_16x16x32_bf16 v[32:35], v[64:67], v[36:39], v[32:35]
	v_exp_f32_e32 v64, v80
	v_exp_f32_e32 v65, v81
	v_exp_f32_e32 v66, v82
	v_exp_f32_e32 v67, v83
	v_exp_f32_e32 v80, v48
	v_exp_f32_e32 v81, v49
	v_exp_f32_e32 v82, v50
	v_mfma_f32_32x32x16_bf16 v[16:31], v[68:71], v[100:103], v[16:31]
	v_exp_f32_e32 v83, v51
	v_cvt_pk_bf16_f32 v48, v64, v65
	v_cvt_pk_bf16_f32 v49, v66, v67
	v_mfma_f32_16x16x32_bf16 v[32:35], v[68:71], v[36:39], v[32:35]
	v_exp_f32_e32 v68, v84
	v_exp_f32_e32 v69, v85
	v_exp_f32_e32 v70, v86
	v_exp_f32_e32 v71, v87
	v_exp_f32_e32 v84, v52
	v_exp_f32_e32 v85, v53
	v_exp_f32_e32 v86, v54
	v_mfma_f32_32x32x16_bf16 v[16:31], v[72:75], v[104:107], v[16:31]
	v_exp_f32_e32 v87, v55
	v_cvt_pk_bf16_f32 v50, v68, v69
	v_cvt_pk_bf16_f32 v51, v70, v71
	v_mfma_f32_16x16x32_bf16 v[32:35], v[72:75], v[36:39], v[32:35]
	v_exp_f32_e32 v72, v88
	v_exp_f32_e32 v73, v89
	v_exp_f32_e32 v74, v90
	v_exp_f32_e32 v75, v91
	v_exp_f32_e32 v88, v56
	v_exp_f32_e32 v89, v57
	v_exp_f32_e32 v90, v58
	v_mfma_f32_32x32x16_bf16 v[16:31], v[76:79], v[108:111], v[16:31]
	v_exp_f32_e32 v91, v59
	v_cvt_pk_bf16_f32 v52, v72, v73
	v_cvt_pk_bf16_f32 v53, v74, v75
	v_mfma_f32_16x16x32_bf16 v[32:35], v[76:79], v[36:39], v[32:35]
	v_exp_f32_e32 v76, v92
	v_exp_f32_e32 v77, v93
	v_exp_f32_e32 v78, v94
	v_exp_f32_e32 v79, v95
	v_exp_f32_e32 v92, v60
	v_exp_f32_e32 v93, v61
	v_exp_f32_e32 v94, v62
	v_cvt_pk_bf16_f32 v54, v76, v77
	v_cvt_pk_bf16_f32 v55, v78, v79
	v_cvt_pk_bf16_f32 v56, v80, v81
	v_cvt_pk_bf16_f32 v57, v82, v83
	v_cvt_pk_bf16_f32 v58, v84, v85
	v_cvt_pk_bf16_f32 v59, v86, v87
	v_cvt_pk_bf16_f32 v60, v88, v89
	v_cvt_pk_bf16_f32 v61, v90, v91
	v_cvt_pk_bf16_f32 v62, v92, v93
	v_cvt_pk_bf16_f32 v63, v94, v63
	ds_read_b64_tr_b16 v[64:65], v190 offset:0
	ds_read_b64_tr_b16 v[66:67], v190 offset:0x400
	ds_read_b64_tr_b16 v[68:69], v190 offset:0x800
	ds_read_b64_tr_b16 v[70:71], v190 offset:0xc00
	ds_read_b64_tr_b16 v[72:73], v190 offset:0x1000
	ds_read_b64_tr_b16 v[74:75], v190 offset:0x1400
	ds_read_b64_tr_b16 v[76:77], v190 offset:0x1800
	ds_read_b64_tr_b16 v[78:79], v190 offset:0x1c00
	s_waitcnt lgkmcnt(0)
; __device__ __forceinline__ int crow(int r, int hi) { return (r & 3) + 8 * (r >> 2) + 4 * hi; }
; template <int DQ, bool WIN, int LDQ, int LDK> ...
;     ...
;     pv(vb0 + SHM_V); lsum_upd();
;     if (WIN) {
;         if (hi == 0) li_l[r32] = m_ref; asm volatile("s_waitcnt lgkmcnt(0)" ::: "memory");
; #pragma unroll
;         for (int r = 0; r < 16; ++r) lsum[r] += __builtin_amdgcn_exp2f(sink_l2 - li_l[crow(r, hi)]);
;     }
;     float rli[16]; bool fin = true;
; #pragma unroll
;     for (int r = 0; r < 16; ++r) { fin = fin && (lsum[r] < ATT_GUARD) && (lsum[r] > 0.f); rli[r] = __builtin_amdgcn_rcpf(lsum[r]); }
;     if (!__all(fin)) { if (lane == 0) *redo_flag = 1; }
	s_nop 0
	v_mfma_f32_32x32x16_bf16 v[0:15], v[48:51], v[64:67], v[0:15]
	ds_read_b64_tr_b16 v[64:65], v190 offset:0x200
	ds_read_b64_tr_b16 v[66:67], v190 offset:0x600
	v_mfma_f32_32x32x16_bf16 v[0:15], v[52:55], v[68:71], v[0:15]
	ds_read_b64_tr_b16 v[68:69], v190 offset:0xa00
	ds_read_b64_tr_b16 v[70:71], v190 offset:0xe00
	v_mfma_f32_32x32x16_bf16 v[0:15], v[56:59], v[72:75], v[0:15]
	ds_read_b64_tr_b16 v[72:73], v190 offset:0x1200
	ds_read_b64_tr_b16 v[74:75], v190 offset:0x1600
	v_mfma_f32_32x32x16_bf16 v[0:15], v[60:63], v[76:79], v[0:15]
	ds_read_b64_tr_b16 v[76:77], v190 offset:0x1a00
	ds_read_b64_tr_b16 v[78:79], v190 offset:0x1e00
	s_waitcnt lgkmcnt(0)
	v_mfma_f32_16x16x32_bf16 v[32:35], v[48:51], v[36:39], v[32:35]
	s_mov_b32 s17, 0x7149f2ca
	v_mfma_f32_16x16x32_bf16 v[32:35], v[52:55], v[36:39], v[32:35]
	v_mfma_f32_16x16x32_bf16 v[32:35], v[56:59], v[36:39], v[32:35]
	v_mfma_f32_16x16x32_bf16 v[32:35], v[60:63], v[36:39], v[32:35]
	v_mfma_f32_32x32x16_bf16 v[16:31], v[48:51], v[64:67], v[16:31]
	v_lshrrev_b32_e32 v96, 4, v189
	v_and_b32_e32 v97, 1, v189
	v_lshlrev_b32_e32 v96, 4, v96
	v_lshl_or_b32 v96, v97, 6, v96
	s_lshl_b32 s4, s16, 3
	s_add_i32 s4, s4, 0xa800
	v_add_u32_e32 v96, s4, v96
	v_lshl_add_u32 v97, v187, 4, s4
	s_nop 1
	ds_write_b128 v96, v[32:35]
	s_waitcnt lgkmcnt(0)
	ds_read_b128 v[32:35], v97
	ds_read_b128 v[36:39], v97 offset:32
	ds_read_b128 v[40:43], v97 offset:64
	ds_read_b128 v[44:47], v97 offset:96
	s_waitcnt lgkmcnt(0)
	v_cmp_gt_f32_e32 vcc, s17, v32
	v_cmp_lt_f32_e64 s[4:5], 0, v32
	s_and_b64 s[18:19], vcc, s[4:5]
	v_cmp_gt_f32_e32 vcc, s17, v33
	v_cmp_lt_f32_e64 s[4:5], 0, v33
	s_and_b64 s[4:5], vcc, s[4:5]
	s_and_b64 s[18:19], s[18:19], s[4:5]
	v_cmp_gt_f32_e32 vcc, s17, v34
	v_cmp_lt_f32_e64 s[4:5], 0, v34
	s_and_b64 s[4:5], vcc, s[4:5]
	s_and_b64 s[18:19], s[18:19], s[4:5]
	v_cmp_gt_f32_e32 vcc, s17, v35
	v_cmp_lt_f32_e64 s[4:5], 0, v35
	s_and_b64 s[4:5], vcc, s[4:5]
	s_and_b64 s[18:19], s[18:19], s[4:5]
	v_cmp_gt_f32_e32 vcc, s17, v36
	v_cmp_lt_f32_e64 s[4:5], 0, v36
	s_and_b64 s[4:5], vcc, s[4:5]
	s_and_b64 s[18:19], s[18:19], s[4:5]
	v_cmp_gt_f32_e32 vcc, s17, v37
	v_cmp_lt_f32_e64 s[4:5], 0, v37
	s_and_b64 s[4:5], vcc, s[4:5]
	s_and_b64 s[18:19], s[18:19], s[4:5]
	v_cmp_gt_f32_e32 vcc, s17, v38
	v_cmp_lt_f32_e64 s[4:5], 0, v38
	s_and_b64 s[4:5], vcc, s[4:5]
	s_and_b64 s[18:19], s[18:19], s[4:5]
	v_cmp_gt_f32_e32 vcc, s17, v39
	v_cmp_lt_f32_e64 s[4:5], 0, v39
	s_and_b64 s[4:5], vcc, s[4:5]
	v_mfma_f32_32x32x16_bf16 v[16:31], v[52:55], v[68:71], v[16:31]
	s_and_b64 s[18:19], s[18:19], s[4:5]
	v_cmp_gt_f32_e32 vcc, s17, v40
	v_cmp_lt_f32_e64 s[4:5], 0, v40
	s_and_b64 s[4:5], vcc, s[4:5]
	s_and_b64 s[18:19], s[18:19], s[4:5]
	v_cmp_gt_f32_e32 vcc, s17, v41
	v_cmp_lt_f32_e64 s[4:5], 0, v41
	s_and_b64 s[4:5], vcc, s[4:5]
	s_and_b64 s[18:19], s[18:19], s[4:5]
	v_cmp_gt_f32_e32 vcc, s17, v42
	v_cmp_lt_f32_e64 s[4:5], 0, v42
	s_and_b64 s[4:5], vcc, s[4:5]
	s_and_b64 s[18:19], s[18:19], s[4:5]
	v_cmp_gt_f32_e32 vcc, s17, v43
	v_cmp_lt_f32_e64 s[4:5], 0, v43
	s_and_b64 s[4:5], vcc, s[4:5]
	v_mfma_f32_32x32x16_bf16 v[16:31], v[56:59], v[72:75], v[16:31]
	s_and_b64 s[18:19], s[18:19], s[4:5]
	v_cmp_gt_f32_e32 vcc, s17, v44
	v_cmp_lt_f32_e64 s[4:5], 0, v44
	s_and_b64 s[4:5], vcc, s[4:5]
	s_and_b64 s[18:19], s[18:19], s[4:5]
	v_cmp_gt_f32_e32 vcc, s17, v45
	v_cmp_lt_f32_e64 s[4:5], 0, v45
	s_and_b64 s[4:5], vcc, s[4:5]
	s_and_b64 s[18:19], s[18:19], s[4:5]
	v_cmp_gt_f32_e32 vcc, s17, v46
	v_cmp_lt_f32_e64 s[4:5], 0, v46
	s_and_b64 s[4:5], vcc, s[4:5]
	s_and_b64 s[18:19], s[18:19], s[4:5]
	v_cmp_gt_f32_e32 vcc, s17, v47
	v_cmp_lt_f32_e64 s[4:5], 0, v47
	s_and_b64 s[4:5], vcc, s[4:5]
	v_mfma_f32_32x32x16_bf16 v[16:31], v[60:63], v[76:79], v[16:31]
	s_and_b64 s[4:5], s[18:19], s[4:5]
	v_cndmask_b32_e64 v48, 0, 1, s[4:5]
	v_cmp_ne_u32_e32 vcc, 0, v48
	s_cmp_eq_u64 vcc, exec
	s_cselect_b64 s[4:5], -1, 0
	v_cndmask_b32_e64 v48, 0, 1, s[4:5]
	v_or_b32_e32 v48, v189, v48
	v_cmp_eq_u32_e32 vcc, 0, v48
	s_and_saveexec_b64 s[4:5], vcc
	s_cbranch_execz .LBB0_1102
	s_add_i32 s17, 0, 0xb000
	s_mov_b64 s[18:19], src_shared_base
	s_cmp_lg_u32 s17, -1
	s_cselect_b32 s17, s17, 0
	s_cselect_b32 s18, s19, 0
	v_mov_b32_e32 v48, s17
	v_mov_b32_e32 v49, s18
	flat_store_dword v[48:49], v170 sc0 sc1
	s_waitcnt vmcnt(0)
